# P3 output-gate section: row's four lanes own chunks part+4cc so gate loads / HM stores are 64B contiguous per row
# speedup vs baseline: 1.0583x; 1.0007x over previous
.LBB0_773:
	s_or_b64 exec, exec, s[0:1]
	s_add_i32 s0, 0, 0x21000
	s_waitcnt lgkmcnt(0)
	s_barrier
	v_lshl_add_u32 v121, v143, 2, s0
	ds_read_b128 v[234:237], v121
	s_waitcnt lgkmcnt(1)
	v_lshlrev_b32_e32 v134, 4, v196
	v_cmp_gt_i32_e64 s[6:7], s86, v132
	v_or_b32_e32 v188, 1, v182
	s_and_b64 s[8:9], s[2:3], s[6:7]
	s_waitcnt lgkmcnt(0)
	v_mul_f32_e32 v48, v48, v234
	v_bfe_u32 v121, v48, 16, 1
	v_mul_f32_e32 v49, v49, v235
	v_add3_u32 v48, v48, v121, s68
	ds_write_b16_d16_hi v222, v48
	v_bfe_u32 v48, v49, 16, 1
	v_add3_u32 v48, v49, v48, s68
	ds_write_b16_d16_hi v225, v48
	v_mul_f32_e32 v48, v50, v236
	v_bfe_u32 v49, v48, 16, 1
	v_add3_u32 v48, v48, v49, s68
	ds_write_b16_d16_hi v229, v48
	v_lshl_add_u32 v48, v113, 2, s0
	ds_read_b128 v[238:241], v48
	v_mul_f32_e32 v48, v51, v237
	v_bfe_u32 v49, v48, 16, 1
	v_add3_u32 v48, v48, v49, s68
	ds_write_b16_d16_hi v211, v48
	s_waitcnt lgkmcnt(1)
	v_mul_f32_e32 v48, v52, v238
	v_bfe_u32 v49, v48, 16, 1
	v_add3_u32 v48, v48, v49, s68
	ds_write_b16_d16_hi v207, v48
	v_mul_f32_e32 v48, v53, v239
	v_bfe_u32 v49, v48, 16, 1
	v_add3_u32 v48, v48, v49, s68
	ds_write_b16_d16_hi v210, v48
	v_mul_f32_e32 v48, v54, v240
	v_bfe_u32 v49, v48, 16, 1
	v_add3_u32 v48, v48, v49, s68
	ds_write_b16_d16_hi v214, v48
	v_lshl_add_u32 v48, v126, 2, s0
	ds_read_b128 v[48:51], v48
	v_mul_f32_e32 v52, v55, v241
	v_bfe_u32 v53, v52, 16, 1
	v_add3_u32 v52, v52, v53, s68
	ds_write_b16_d16_hi v213, v52
	s_waitcnt lgkmcnt(1)
	v_mul_f32_e32 v52, v56, v48
	v_bfe_u32 v53, v52, 16, 1
	v_add3_u32 v52, v52, v53, s68
	ds_write_b16_d16_hi v215, v52
	v_mul_f32_e32 v52, v57, v49
	v_bfe_u32 v53, v52, 16, 1
	v_add3_u32 v52, v52, v53, s68
	ds_write_b16_d16_hi v217, v52
	v_mul_f32_e32 v52, v58, v50
	v_bfe_u32 v53, v52, 16, 1
	v_add3_u32 v52, v52, v53, s68
	ds_write_b16_d16_hi v219, v52
	v_lshl_add_u32 v52, v123, 2, s0
	ds_read_b128 v[52:55], v52
	v_mul_f32_e32 v56, v59, v51
	v_bfe_u32 v57, v56, 16, 1
	v_add3_u32 v56, v56, v57, s68
	ds_write_b16_d16_hi v204, v56
	s_waitcnt lgkmcnt(1)
	v_mul_f32_e32 v56, v60, v52
	v_bfe_u32 v57, v56, 16, 1
	v_add3_u32 v56, v56, v57, s68
	ds_write_b16_d16_hi v202, v56
	v_mul_f32_e32 v56, v61, v53
	v_bfe_u32 v57, v56, 16, 1
	v_add3_u32 v56, v56, v57, s68
	ds_write_b16_d16_hi v203, v56
	v_mul_f32_e32 v56, v62, v54
	v_bfe_u32 v57, v56, 16, 1
	v_add3_u32 v56, v56, v57, s68
	ds_write_b16_d16_hi v205, v56
	v_mul_f32_e32 v56, v63, v55
	v_bfe_u32 v57, v56, 16, 1
	v_add3_u32 v56, v56, v57, s68
	v_mul_f32_e32 v32, v32, v234
	ds_write_b16_d16_hi v206, v56
	v_bfe_u32 v56, v32, 16, 1
	v_add3_u32 v32, v32, v56, s68
	ds_write_b16_d16_hi v208, v32
	v_mul_f32_e32 v32, v33, v235
	v_bfe_u32 v33, v32, 16, 1
	v_add3_u32 v32, v32, v33, s68
	ds_write_b16_d16_hi v209, v32
	v_mul_f32_e32 v32, v34, v236
	v_bfe_u32 v33, v32, 16, 1
	v_add3_u32 v32, v32, v33, s68
	ds_write_b16_d16_hi v212, v32
	v_mul_f32_e32 v32, v35, v237
	v_bfe_u32 v33, v32, 16, 1
	v_add3_u32 v32, v32, v33, s68
	ds_write_b16_d16_hi v216, v32
	v_mul_f32_e32 v32, v36, v238
	v_bfe_u32 v33, v32, 16, 1
	v_add3_u32 v32, v32, v33, s68
	ds_write_b16_d16_hi v218, v32
	v_mul_f32_e32 v32, v37, v239
	v_bfe_u32 v33, v32, 16, 1
	v_add3_u32 v32, v32, v33, s68
	ds_write_b16_d16_hi v220, v32
	v_mul_f32_e32 v32, v38, v240
	v_bfe_u32 v33, v32, 16, 1
	v_add3_u32 v32, v32, v33, s68
	ds_write_b16_d16_hi v221, v32
	v_mul_f32_e32 v32, v39, v241
	v_bfe_u32 v33, v32, 16, 1
	v_add3_u32 v32, v32, v33, s68
	ds_write_b16_d16_hi v223, v32
	v_mul_f32_e32 v32, v40, v48
	v_bfe_u32 v33, v32, 16, 1
	v_add3_u32 v32, v32, v33, s68
	ds_write_b16_d16_hi v224, v32
	v_mul_f32_e32 v32, v41, v49
	v_bfe_u32 v33, v32, 16, 1
	v_add3_u32 v32, v32, v33, s68
	ds_write_b16_d16_hi v226, v32
	v_mul_f32_e32 v32, v42, v50
	v_bfe_u32 v33, v32, 16, 1
	v_add3_u32 v32, v32, v33, s68
	ds_write_b16_d16_hi v227, v32
	v_mul_f32_e32 v32, v43, v51
	v_bfe_u32 v33, v32, 16, 1
	v_add3_u32 v32, v32, v33, s68
	ds_write_b16_d16_hi v228, v32
	v_mul_f32_e32 v32, v44, v52
	v_bfe_u32 v33, v32, 16, 1
	v_add3_u32 v32, v32, v33, s68
	ds_write_b16_d16_hi v230, v32
	v_mul_f32_e32 v32, v45, v53
	v_bfe_u32 v33, v32, 16, 1
	v_add3_u32 v32, v32, v33, s68
	ds_write_b16_d16_hi v231, v32
	v_mul_f32_e32 v32, v46, v54
	v_bfe_u32 v33, v32, 16, 1
	v_add3_u32 v32, v32, v33, s68
	ds_write_b16_d16_hi v232, v32
	v_mul_f32_e32 v32, v47, v55
	v_bfe_u32 v33, v32, 16, 1
	v_add3_u32 v32, v32, v33, s68
	v_ashrrev_i32_e32 v121, 31, v120
	ds_write_b16_d16_hi v233, v32
	v_lshl_add_u64 v[32:33], s[66:67], 0, v[120:121]
	v_lshlrev_b64 v[34:35], 13, v[32:33]
	v_lshl_add_u64 v[38:39], s[52:53], 0, v[34:35]
	s_waitcnt lgkmcnt(0)
	s_barrier
	v_lshl_add_u64 v[34:35], v[38:39], 0, v[134:135]
	global_load_dwordx4 v[40:43], v[34:35], off offset:3072
	v_lshlrev_b32_e32 v121, 5, v196
	global_load_dwordx4 v[48:51], v121, s[18:19]
	v_bfe_u32 v246, v120, 2, 2
	v_xor_b32_e32 v246, v246, v196
	v_lshlrev_b32_e32 v247, 8, v120
	v_lshl_or_b32 v247, v246, 4, v247
	v_and_b32_e32 v246, 3, v120
	v_lshl_or_b32 v247, v246, 6, v247
	v_xor_b32_e32 v248, 64, v247
	v_xor_b32_e32 v249, 0x80, v247
	v_xor_b32_e32 v250, 0xc0, v247
	ds_read_b128 v[44:47], v250
	ds_read_b128 v[52:55], v247
	ds_read_b128 v[56:59], v248
	ds_read_b128 v[60:63], v249
	global_load_dwordx4 v[200:203], v121, s[18:19] offset:16
	s_waitcnt lgkmcnt(3)
	v_and_b32_e32 v34, 0xffff0000, v46
	v_lshlrev_b32_e32 v35, 16, v46
	v_and_b32_e32 v36, 0xffff0000, v47
	v_lshlrev_b32_e32 v37, 16, v47
	s_waitcnt lgkmcnt(2)
	v_lshlrev_b32_e32 v209, 16, v53
	v_lshlrev_b32_e32 v208, 16, v52
	v_and_b32_e32 v53, 0xffff0000, v53
	v_and_b32_e32 v52, 0xffff0000, v52
	v_pk_mul_f32 v[210:211], v[208:209], v[208:209]
	v_pk_mul_f32 v[212:213], v[52:53], v[52:53]
	v_lshlrev_b32_e32 v221, 16, v55
	v_lshlrev_b32_e32 v220, 16, v54
	v_and_b32_e32 v55, 0xffff0000, v55
	v_and_b32_e32 v54, 0xffff0000, v54
	v_pk_mul_f32 v[222:223], v[220:221], v[220:221]
	v_pk_mul_f32 v[224:225], v[54:55], v[54:55]
	s_waitcnt lgkmcnt(1)
	v_lshlrev_b32_e32 v235, 16, v57
	v_lshlrev_b32_e32 v234, 16, v56
	v_and_b32_e32 v237, 0xffff0000, v57
	v_and_b32_e32 v236, 0xffff0000, v56
	v_pk_mul_f32 v[56:57], v[234:235], v[234:235]
	v_pk_mul_f32 v[238:239], v[236:237], v[236:237]
	v_lshlrev_b32_e32 v241, 16, v59
	v_lshlrev_b32_e32 v240, 16, v58
	v_and_b32_e32 v243, 0xffff0000, v59
	v_and_b32_e32 v242, 0xffff0000, v58
	v_pk_mul_f32 v[58:59], v[240:241], v[240:241]
	v_pk_mul_f32 v[244:245], v[242:243], v[242:243]
	s_waitcnt lgkmcnt(0)
	v_lshlrev_b32_e32 v247, 16, v61
	v_lshlrev_b32_e32 v246, 16, v60
	v_and_b32_e32 v249, 0xffff0000, v61
	v_and_b32_e32 v248, 0xffff0000, v60
	v_pk_mul_f32 v[60:61], v[246:247], v[246:247]
	v_pk_mul_f32 v[250:251], v[248:249], v[248:249]
	v_pk_mul_f32 v[204:205], v[34:35], v[34:35]
	v_pk_mul_f32 v[206:207], v[36:37], v[36:37]
	v_lshlrev_b64 v[32:33], 11, v[32:33]
	v_lshl_add_u64 v[32:33], s[54:55], 0, v[32:33]
	s_waitcnt vmcnt(2)
	v_lshlrev_b32_e32 v46, 16, v40
	v_mul_f32_e32 v47, 0xbfb8aa3b, v46
	v_exp_f32_e32 v136, v47
	v_lshlrev_b32_e32 v47, 16, v41
	v_and_b32_e32 v41, 0xffff0000, v41
	v_and_b32_e32 v40, 0xffff0000, v40
	v_mul_f32_e32 v137, 0xbfb8aa3b, v40
	v_mul_f32_e32 v121, 0xbfb8aa3b, v41
	v_exp_f32_e32 v137, v137
	v_exp_f32_e32 v121, v121
	v_mul_f32_e32 v189, 0xbfb8aa3b, v47
	v_exp_f32_e32 v189, v189
	v_add_f32_e32 v136, 1.0, v136
	v_rcp_f32_e32 v214, v136
	v_add_f32_e32 v136, 1.0, v137
	s_waitcnt vmcnt(1)
	v_mov_b32_e32 v218, v48
	v_add_f32_e32 v48, 1.0, v121
	v_rcp_f32_e32 v216, v136
	v_rcp_f32_e32 v217, v48
	v_add_f32_e32 v121, v210, v212
	v_add_f32_e32 v136, 1.0, v189
	v_add_f32_e32 v121, v211, v121
	v_rcp_f32_e32 v215, v136
	v_add_f32_e32 v121, v213, v121
	v_add_f32_e32 v121, v222, v121
	v_pk_mul_f32 v[40:41], v[216:217], v[40:41]
	v_add_f32_e32 v121, v224, v121
	v_cndmask_b32_e64 v216, v40, v216, s[2:3]
	v_lshlrev_b32_e32 v40, 16, v42
	v_add_f32_e32 v121, v223, v121
	v_pk_mul_f32 v[46:47], v[214:215], v[46:47]
	v_cndmask_b32_e64 v217, v41, v217, s[2:3]
	v_mul_f32_e32 v41, 0xbfb8aa3b, v40
	v_add_f32_e32 v121, v225, v121
	v_cndmask_b32_e64 v214, v46, v214, s[2:3]
	v_exp_f32_e32 v46, v41
	v_lshlrev_b32_e32 v41, 16, v43
	v_add_f32_e32 v56, v56, v121
	v_and_b32_e32 v227, 0xffff0000, v43
	v_mul_f32_e32 v43, 0xbfb8aa3b, v41
	v_add_f32_e32 v56, v238, v56
	v_exp_f32_e32 v43, v43
	v_add_f32_e32 v56, v57, v56
	v_add_f32_e32 v56, v239, v56
	v_add_f32_e32 v56, v58, v56
	v_add_f32_e32 v56, v244, v56
	v_add_f32_e32 v43, 1.0, v43
	v_add_f32_e32 v56, v59, v56
	v_and_b32_e32 v226, 0xffff0000, v42
	v_add_f32_e32 v42, 1.0, v46
	v_rcp_f32_e32 v229, v43
	v_mul_f32_e32 v43, 0xbfb8aa3b, v227
	v_add_f32_e32 v56, v245, v56
	v_rcp_f32_e32 v228, v42
	v_exp_f32_e32 v43, v43
	v_add_f32_e32 v56, v60, v56
	v_add_f32_e32 v56, v250, v56
	v_mov_b32_e32 v219, v50
	v_mov_b32_e32 v50, v49
	v_mul_f32_e32 v42, 0xbfb8aa3b, v226
	v_lshlrev_b32_e32 v49, 16, v63
	v_lshlrev_b32_e32 v48, 16, v62
	v_add_f32_e32 v56, v61, v56
	v_cndmask_b32_e64 v215, v47, v215, s[2:3]
	v_exp_f32_e32 v42, v42
	v_and_b32_e32 v47, 0xffff0000, v63
	v_and_b32_e32 v46, 0xffff0000, v62
	v_pk_mul_f32 v[62:63], v[48:49], v[48:49]
	v_add_f32_e32 v56, v251, v56
	v_pk_mul_f32 v[232:233], v[228:229], v[40:41]
	v_add_f32_e32 v40, 1.0, v43
	v_pk_mul_f32 v[252:253], v[46:47], v[46:47]
	v_add_f32_e32 v56, v62, v56
	v_rcp_f32_e32 v231, v40
	v_lshlrev_b32_e32 v136, 16, v44
	v_and_b32_e32 v40, 0xffff0000, v44
	v_add_f32_e32 v56, v252, v56
	v_lshlrev_b32_e32 v137, 16, v45
	v_and_b32_e32 v41, 0xffff0000, v45
	v_mov_b32_e32 v44, v40
	v_mov_b32_e32 v45, v136
	v_add_f32_e32 v56, v63, v56
	v_add_f32_e32 v42, 1.0, v42
	v_pk_mul_f32 v[44:45], v[44:45], v[44:45]
	v_add_f32_e32 v56, v253, v56
	v_rcp_f32_e32 v230, v42
	v_mov_b32_e32 v42, v41
	v_mov_b32_e32 v43, v137
	v_add_f32_e32 v45, v45, v56
	v_pk_mul_f32 v[42:43], v[42:43], v[42:43]
	v_add_f32_e32 v44, v44, v45
	v_add_f32_e32 v43, v43, v44
	v_add_f32_e32 v42, v42, v43
	v_add_f32_e32 v42, v205, v42
	v_add_f32_e32 v42, v204, v42
	v_add_f32_e32 v42, v207, v42
	v_add_f32_e32 v56, v206, v42
	ds_bpermute_b32 v58, v197, v56
	v_pk_mul_f32 v[44:45], v[230:231], v[226:227]
	s_waitcnt vmcnt(0)
	v_mov_b32_e32 v59, v202
	v_cndmask_b32_e64 v57, v45, v231, s[2:3]
	v_cndmask_b32_e64 v43, v233, v229, s[2:3]
	s_waitcnt lgkmcnt(0)
	v_add_f32_e32 v45, v56, v58
	ds_bpermute_b32 v60, v198, v45
	v_cndmask_b32_e64 v56, v44, v230, s[2:3]
	v_mov_b32_e32 v58, v200
	v_cndmask_b32_e64 v42, v232, v228, s[2:3]
	v_mov_b32_e32 v202, v201
	s_waitcnt lgkmcnt(0)
	v_add_f32_e32 v44, v45, v60
	v_fmamk_f32 v44, v44, 0x3c000000, v133
	v_cmp_gt_f32_e32 vcc, s85, v44
	v_mul_f32_e32 v45, 0x4b800000, v44
	v_lshl_add_u64 v[60:61], v[32:33], 0, v[134:135]
	v_cndmask_b32_e32 v44, v44, v45, vcc
	v_rsq_f32_e32 v44, v44
	v_and_b32_e32 v134, -4, v195
	v_lshlrev_b32_e32 v134, 2, v134
	v_add_u32_e32 v134, 0x40, v134
	v_lshl_add_u64 v[62:63], v[38:39], 0, v[134:135]
	v_mul_f32_e32 v45, 0x45800000, v44
	v_cndmask_b32_e32 v44, v44, v45, vcc
	v_pk_mul_f32 v[52:53], v[44:45], v[52:53] op_sel_hi:[0,1]
	v_pk_mul_f32 v[50:51], v[50:51], v[52:53]
	v_pk_mul_f32 v[52:53], v[44:45], v[220:221] op_sel_hi:[0,1]
	v_pk_mul_f32 v[52:53], v[58:59], v[52:53]
	v_pk_mul_f32 v[196:197], v[44:45], v[208:209] op_sel_hi:[0,1]
	v_pk_mul_f32 v[42:43], v[42:43], v[52:53]
	v_pk_mul_f32 v[52:53], v[44:45], v[54:55] op_sel_hi:[0,1]
	v_pk_mul_f32 v[52:53], v[202:203], v[52:53]
	v_pk_mul_f32 v[196:197], v[218:219], v[196:197]
	v_pk_mul_f32 v[50:51], v[216:217], v[50:51]
	v_pk_mul_f32 v[52:53], v[56:57], v[52:53]
	v_pk_mul_f32 v[196:197], v[214:215], v[196:197]
	v_bfe_u32 v45, v53, 16, 1
	v_bfe_u32 v54, v52, 16, 1
	v_bfe_u32 v55, v51, 16, 1
	v_bfe_u32 v56, v50, 16, 1
	v_add3_u32 v50, v50, v56, s68
	v_add3_u32 v51, v51, v55, s68
	v_add3_u32 v52, v52, v54, s68
	v_add3_u32 v45, v53, v45, s68
	v_bfe_u32 v53, v196, 16, 1
	v_bfe_u32 v54, v197, 16, 1
	v_bfe_u32 v55, v42, 16, 1
	v_bfe_u32 v56, v43, 16, 1
	v_add3_u32 v43, v43, v56, s68
	v_add3_u32 v42, v42, v55, s68
	v_add3_u32 v54, v197, v54, s68
	v_add3_u32 v53, v196, v53, s68
	v_lshrrev_b32_e32 v55, 16, v53
	v_lshrrev_b32_e32 v54, 16, v54
	v_lshrrev_b32_e32 v42, 16, v42
	v_lshrrev_b32_e32 v43, 16, v43
	v_and_or_b32 v53, v45, s82, v43
	v_and_or_b32 v52, v52, s82, v42
	v_and_or_b32 v51, v51, s82, v54
	v_and_or_b32 v50, v50, s82, v55
	v_and_b32_e32 v60, 0xffffffc0, v191
	ds_write_b128 v60, v[50:53]
	global_load_dwordx4 v[50:53], v[62:63], off offset:3072
	v_and_b32_e32 v42, -4, v195
	v_lshlrev_b32_e32 v42, 3, v42
	v_add_u32_e32 v42, 0x80, v42
	global_load_dwordx4 v[54:57], v42, s[18:19]
	global_load_dwordx4 v[58:61], v42, s[18:19] offset:16
	v_lshl_add_u64 v[42:43], v[32:33], 0, v[134:135]
	v_and_b32_e32 v134, -4, v194
	v_lshlrev_b32_e32 v134, 2, v134
	v_add_u32_e32 v134, 0x80, v134
	v_lshl_add_u64 v[62:63], v[38:39], 0, v[134:135]
	s_waitcnt vmcnt(2)
	v_lshlrev_b32_e32 v196, 16, v50
	v_and_b32_e32 v50, 0xffff0000, v50
	v_mul_f32_e32 v45, 0xbfb8aa3b, v196
	v_lshlrev_b32_e32 v197, 16, v51
	v_exp_f32_e32 v45, v45
	v_mul_f32_e32 v121, 0xbfb8aa3b, v50
	v_exp_f32_e32 v121, v121
	v_mul_f32_e32 v189, 0xbfb8aa3b, v197
	v_exp_f32_e32 v189, v189
	v_add_f32_e32 v45, 1.0, v45
	v_rcp_f32_e32 v200, v45
	v_add_f32_e32 v45, 1.0, v121
	v_and_b32_e32 v51, 0xffff0000, v51
	v_rcp_f32_e32 v202, v45
	v_add_f32_e32 v45, 1.0, v189
	v_rcp_f32_e32 v201, v45
	v_pk_mul_f32 v[204:205], v[44:45], v[234:235] op_sel_hi:[0,1]
	v_mul_f32_e32 v45, 0xbfb8aa3b, v51
	v_exp_f32_e32 v45, v45
	v_pk_mul_f32 v[196:197], v[200:201], v[196:197]
	v_lshlrev_b32_e32 v198, 16, v52
	s_waitcnt vmcnt(1)
	v_mov_b32_e32 v207, v56
	v_add_f32_e32 v45, 1.0, v45
	v_rcp_f32_e32 v203, v45
	v_cndmask_b32_e64 v197, v197, v201, s[2:3]
	v_cndmask_b32_e64 v196, v196, v200, s[2:3]
	v_pk_mul_f32 v[200:201], v[44:45], v[236:237] op_sel_hi:[0,1]
	v_mov_b32_e32 v56, v55
	v_pk_mul_f32 v[50:51], v[202:203], v[50:51]
	v_and_b32_e32 v52, 0xffff0000, v52
	v_mov_b32_e32 v206, v54
	v_pk_mul_f32 v[54:55], v[56:57], v[200:201]
	v_mul_f32_e32 v45, 0xbfb8aa3b, v198
	v_cndmask_b32_e64 v51, v51, v203, s[2:3]
	v_cndmask_b32_e64 v50, v50, v202, s[2:3]
	v_lshlrev_b32_e32 v199, 16, v53
	v_exp_f32_e32 v45, v45
	v_pk_mul_f32 v[50:51], v[50:51], v[54:55]
	v_mul_f32_e32 v54, 0xbfb8aa3b, v52
	v_exp_f32_e32 v55, v54
	v_mul_f32_e32 v54, 0xbfb8aa3b, v199
	v_exp_f32_e32 v57, v54
	v_add_f32_e32 v45, 1.0, v45
	v_rcp_f32_e32 v54, v45
	v_add_f32_e32 v45, 1.0, v55
	v_and_b32_e32 v53, 0xffff0000, v53
	v_rcp_f32_e32 v56, v45
	v_add_f32_e32 v45, 1.0, v57
	v_rcp_f32_e32 v55, v45
	v_pk_mul_f32 v[200:201], v[44:45], v[240:241] op_sel_hi:[0,1]
	v_mul_f32_e32 v45, 0xbfb8aa3b, v53
	v_exp_f32_e32 v45, v45
	v_pk_mul_f32 v[198:199], v[54:55], v[198:199]
	s_waitcnt vmcnt(0)
	v_mov_b32_e32 v203, v60
	v_cndmask_b32_e64 v55, v199, v55, s[2:3]
	v_add_f32_e32 v45, 1.0, v45
	v_rcp_f32_e32 v57, v45
	v_cndmask_b32_e64 v54, v198, v54, s[2:3]
	v_pk_mul_f32 v[198:199], v[44:45], v[242:243] op_sel_hi:[0,1]
	v_mov_b32_e32 v60, v59
	v_pk_mul_f32 v[52:53], v[56:57], v[52:53]
	v_mov_b32_e32 v202, v58
	v_pk_mul_f32 v[58:59], v[60:61], v[198:199]
	v_cndmask_b32_e64 v53, v53, v57, s[2:3]
	v_cndmask_b32_e64 v52, v52, v56, s[2:3]
	v_pk_mul_f32 v[204:205], v[206:207], v[204:205]
	v_pk_mul_f32 v[200:201], v[202:203], v[200:201]
	v_pk_mul_f32 v[52:53], v[52:53], v[58:59]
	v_pk_mul_f32 v[196:197], v[196:197], v[204:205]
	v_pk_mul_f32 v[54:55], v[54:55], v[200:201]
	v_bfe_u32 v45, v53, 16, 1
	v_bfe_u32 v56, v52, 16, 1
	v_bfe_u32 v57, v51, 16, 1
	v_bfe_u32 v58, v50, 16, 1
	v_add3_u32 v50, v50, v58, s68
	v_add3_u32 v51, v51, v57, s68
	v_add3_u32 v52, v52, v56, s68
	v_add3_u32 v45, v53, v45, s68
	v_bfe_u32 v53, v196, 16, 1
	v_bfe_u32 v56, v197, 16, 1
	v_bfe_u32 v57, v54, 16, 1
	v_bfe_u32 v58, v55, 16, 1
	v_add3_u32 v55, v55, v58, s68
	v_add3_u32 v54, v54, v57, s68
	v_add3_u32 v56, v197, v56, s68
	v_add3_u32 v53, v196, v53, s68
	v_lshrrev_b32_e32 v57, 16, v53
	v_lshrrev_b32_e32 v56, 16, v56
	v_lshrrev_b32_e32 v54, 16, v54
	v_lshrrev_b32_e32 v53, 16, v55
	v_and_or_b32 v53, v45, s82, v53
	v_and_or_b32 v52, v52, s82, v54
	v_and_or_b32 v51, v51, s82, v56
	v_and_or_b32 v50, v50, s82, v57
	v_and_b32_e32 v42, 0xffffffc0, v191
	ds_write_b128 v42, v[50:53] offset:16
	global_load_dwordx4 v[50:53], v[62:63], off offset:3072
	v_and_b32_e32 v42, -4, v194
	v_lshlrev_b32_e32 v42, 3, v42
	v_add_u32_e32 v42, 0x100, v42
	global_load_dwordx4 v[54:57], v42, s[18:19]
	global_load_dwordx4 v[58:61], v42, s[18:19] offset:16
	v_lshl_add_u64 v[42:43], v[32:33], 0, v[134:135]
	v_and_b32_e32 v134, -4, v193
	v_lshlrev_b32_e32 v134, 2, v134
	v_add_u32_e32 v134, 0xc0, v134
	v_lshl_add_u64 v[38:39], v[38:39], 0, v[134:135]
	v_lshl_add_u64 v[32:33], v[32:33], 0, v[134:135]
	s_waitcnt vmcnt(2)
	v_lshlrev_b32_e32 v62, 16, v50
	v_and_b32_e32 v50, 0xffff0000, v50
	v_mul_f32_e32 v45, 0xbfb8aa3b, v62
	v_lshlrev_b32_e32 v63, 16, v51
	v_exp_f32_e32 v45, v45
	v_mul_f32_e32 v121, 0xbfb8aa3b, v50
	v_exp_f32_e32 v121, v121
	v_mul_f32_e32 v189, 0xbfb8aa3b, v63
	v_exp_f32_e32 v189, v189
	v_add_f32_e32 v45, 1.0, v45
	v_rcp_f32_e32 v196, v45
	v_add_f32_e32 v45, 1.0, v121
	v_and_b32_e32 v51, 0xffff0000, v51
	v_rcp_f32_e32 v198, v45
	v_add_f32_e32 v45, 1.0, v189
	v_rcp_f32_e32 v197, v45
	v_pk_mul_f32 v[200:201], v[44:45], v[246:247] op_sel_hi:[0,1]
	v_mul_f32_e32 v45, 0xbfb8aa3b, v51
	v_exp_f32_e32 v45, v45
	v_pk_mul_f32 v[62:63], v[196:197], v[62:63]
	v_lshlrev_b32_e32 v194, 16, v52
	s_waitcnt vmcnt(1)
	v_mov_b32_e32 v203, v56
	v_add_f32_e32 v45, 1.0, v45
	v_rcp_f32_e32 v199, v45
	v_cndmask_b32_e64 v63, v63, v197, s[2:3]
	v_cndmask_b32_e64 v62, v62, v196, s[2:3]
	v_pk_mul_f32 v[196:197], v[44:45], v[248:249] op_sel_hi:[0,1]
	v_mov_b32_e32 v56, v55
	v_pk_mul_f32 v[50:51], v[198:199], v[50:51]
	v_and_b32_e32 v52, 0xffff0000, v52
	v_mov_b32_e32 v202, v54
	v_pk_mul_f32 v[54:55], v[56:57], v[196:197]
	v_mul_f32_e32 v45, 0xbfb8aa3b, v194
	v_cndmask_b32_e64 v51, v51, v199, s[2:3]
	v_cndmask_b32_e64 v50, v50, v198, s[2:3]
	v_lshlrev_b32_e32 v195, 16, v53
	v_exp_f32_e32 v45, v45
	v_pk_mul_f32 v[50:51], v[50:51], v[54:55]
	v_mul_f32_e32 v54, 0xbfb8aa3b, v52
	v_exp_f32_e32 v55, v54
	v_mul_f32_e32 v54, 0xbfb8aa3b, v195
	v_exp_f32_e32 v57, v54
	v_add_f32_e32 v45, 1.0, v45
	v_rcp_f32_e32 v54, v45
	v_add_f32_e32 v45, 1.0, v55
	v_and_b32_e32 v53, 0xffff0000, v53
	v_rcp_f32_e32 v56, v45
	v_add_f32_e32 v45, 1.0, v57
	v_rcp_f32_e32 v55, v45
	v_pk_mul_f32 v[48:49], v[44:45], v[48:49] op_sel_hi:[0,1]
	v_mul_f32_e32 v45, 0xbfb8aa3b, v53
	v_exp_f32_e32 v45, v45
	s_waitcnt vmcnt(0)
	v_mov_b32_e32 v197, v60
	v_mov_b32_e32 v60, v59
	v_mov_b32_e32 v196, v58
	v_add_f32_e32 v45, 1.0, v45
	v_rcp_f32_e32 v57, v45
	v_pk_mul_f32 v[46:47], v[44:45], v[46:47] op_sel_hi:[0,1]
	v_pk_mul_f32 v[194:195], v[54:55], v[194:195]
	v_pk_mul_f32 v[46:47], v[60:61], v[46:47]
	v_pk_mul_f32 v[52:53], v[56:57], v[52:53]
	v_pk_mul_f32 v[200:201], v[202:203], v[200:201]
	v_cndmask_b32_e64 v53, v53, v57, s[2:3]
	v_cndmask_b32_e64 v52, v52, v56, s[2:3]
	v_pk_mul_f32 v[48:49], v[196:197], v[48:49]
	v_cndmask_b32_e64 v55, v195, v55, s[2:3]
	v_cndmask_b32_e64 v54, v194, v54, s[2:3]
	v_pk_mul_f32 v[46:47], v[52:53], v[46:47]
	v_pk_mul_f32 v[62:63], v[62:63], v[200:201]
	v_pk_mul_f32 v[48:49], v[54:55], v[48:49]
	v_bfe_u32 v45, v47, 16, 1
	v_bfe_u32 v52, v46, 16, 1
	v_bfe_u32 v53, v51, 16, 1
	v_bfe_u32 v54, v50, 16, 1
	v_add3_u32 v50, v50, v54, s68
	v_add3_u32 v51, v51, v53, s68
	v_add3_u32 v46, v46, v52, s68
	v_add3_u32 v45, v47, v45, s68
	v_bfe_u32 v47, v62, 16, 1
	v_bfe_u32 v52, v63, 16, 1
	v_bfe_u32 v53, v48, 16, 1
	v_bfe_u32 v54, v49, 16, 1
	v_add3_u32 v49, v49, v54, s68
	v_add3_u32 v48, v48, v53, s68
	v_add3_u32 v52, v63, v52, s68
	v_add3_u32 v47, v62, v47, s68
	v_lshrrev_b32_e32 v53, 16, v47
	v_lshrrev_b32_e32 v47, 16, v52
	v_lshrrev_b32_e32 v48, 16, v48
	v_lshrrev_b32_e32 v49, 16, v49
	v_and_or_b32 v49, v45, s82, v49
	v_and_or_b32 v48, v46, s82, v48
	v_and_or_b32 v47, v51, s82, v47
	v_and_or_b32 v46, v50, s82, v53
	v_and_b32_e32 v42, 0xffffffc0, v191
	ds_write_b128 v42, v[46:49] offset:32
	global_load_dwordx4 v[46:49], v[38:39], off offset:3072
	v_and_b32_e32 v38, -4, v193
	v_lshlrev_b32_e32 v38, 3, v38
	v_add_u32_e32 v38, 0x180, v38
	global_load_dwordx4 v[50:53], v38, s[18:19]
	global_load_dwordx4 v[54:57], v38, s[18:19] offset:16
	s_waitcnt vmcnt(2)
	v_lshlrev_b32_e32 v38, 16, v46
	v_mul_f32_e32 v39, 0xbfb8aa3b, v38
	v_and_b32_e32 v42, 0xffff0000, v46
	v_exp_f32_e32 v45, v39
	v_lshlrev_b32_e32 v39, 16, v47
	v_mul_f32_e32 v46, 0xbfb8aa3b, v42
	v_and_b32_e32 v43, 0xffff0000, v47
	v_exp_f32_e32 v47, v46
	v_mul_f32_e32 v46, 0xbfb8aa3b, v39
	v_exp_f32_e32 v59, v46
	v_add_f32_e32 v45, 1.0, v45
	v_rcp_f32_e32 v46, v45
	v_add_f32_e32 v45, 1.0, v47
	v_rcp_f32_e32 v58, v45
	v_add_f32_e32 v45, 1.0, v59
	v_rcp_f32_e32 v47, v45
	v_pk_mul_f32 v[60:61], v[44:45], v[136:137] op_sel_hi:[0,1]
	v_mul_f32_e32 v45, 0xbfb8aa3b, v43
	v_exp_f32_e32 v45, v45
	s_waitcnt vmcnt(1)
	v_mov_b32_e32 v63, v52
	v_mov_b32_e32 v52, v51
	v_pk_mul_f32 v[38:39], v[46:47], v[38:39]
	v_add_f32_e32 v45, 1.0, v45
	v_rcp_f32_e32 v59, v45
	v_pk_mul_f32 v[40:41], v[44:45], v[40:41] op_sel_hi:[0,1]
	v_pk_mul_f32 v[40:41], v[52:53], v[40:41]
	v_cndmask_b32_e64 v39, v39, v47, s[2:3]
	v_pk_mul_f32 v[42:43], v[58:59], v[42:43]
	v_cndmask_b32_e64 v38, v38, v46, s[2:3]
	v_cndmask_b32_e64 v43, v43, v59, s[2:3]
	v_cndmask_b32_e64 v42, v42, v58, s[2:3]
	v_pk_mul_f32 v[40:41], v[42:43], v[40:41]
	v_lshlrev_b32_e32 v42, 16, v48
	v_mul_f32_e32 v43, 0xbfb8aa3b, v42
	v_and_b32_e32 v47, 0xffff0000, v49
	v_and_b32_e32 v46, 0xffff0000, v48
	v_exp_f32_e32 v45, v43
	v_lshlrev_b32_e32 v43, 16, v49
	v_mul_f32_e32 v48, 0xbfb8aa3b, v46
	v_mov_b32_e32 v52, v35
	v_mul_f32_e32 v35, 0xbfb8aa3b, v47
	v_exp_f32_e32 v49, v48
	v_mul_f32_e32 v48, 0xbfb8aa3b, v43
	v_exp_f32_e32 v35, v35
	v_exp_f32_e32 v51, v48
	v_add_f32_e32 v45, 1.0, v45
	v_rcp_f32_e32 v48, v45
	v_add_f32_e32 v45, 1.0, v49
	v_add_f32_e32 v35, 1.0, v35
	v_mov_b32_e32 v62, v50
	v_rcp_f32_e32 v50, v45
	v_add_f32_e32 v45, 1.0, v51
	v_rcp_f32_e32 v51, v35
	v_rcp_f32_e32 v49, v45
	v_mov_b32_e32 v35, v36
	v_mov_b32_e32 v53, v37
	s_waitcnt vmcnt(0)
	v_mov_b32_e32 v59, v56
	v_pk_mul_f32 v[34:35], v[44:45], v[34:35] op_sel_hi:[0,1]
	v_mov_b32_e32 v56, v55
	v_pk_mul_f32 v[36:37], v[50:51], v[46:47]
	v_pk_mul_f32 v[52:53], v[44:45], v[52:53] op_sel_hi:[0,1]
	v_mov_b32_e32 v58, v54
	v_pk_mul_f32 v[42:43], v[48:49], v[42:43]
	v_pk_mul_f32 v[34:35], v[56:57], v[34:35]
	v_cndmask_b32_e64 v37, v37, v51, s[2:3]
	v_cndmask_b32_e64 v36, v36, v50, s[2:3]
	v_pk_mul_f32 v[60:61], v[62:63], v[60:61]
	v_pk_mul_f32 v[52:53], v[58:59], v[52:53]
	v_cndmask_b32_e64 v43, v43, v49, s[2:3]
	v_cndmask_b32_e64 v42, v42, v48, s[2:3]
	v_pk_mul_f32 v[34:35], v[36:37], v[34:35]
	v_pk_mul_f32 v[38:39], v[38:39], v[60:61]
	v_pk_mul_f32 v[42:43], v[42:43], v[52:53]
	v_bfe_u32 v36, v35, 16, 1
	v_bfe_u32 v37, v34, 16, 1
	v_bfe_u32 v44, v41, 16, 1
	v_bfe_u32 v45, v40, 16, 1
	v_add3_u32 v40, v40, v45, s68
	v_add3_u32 v41, v41, v44, s68
	v_add3_u32 v34, v34, v37, s68
	v_add3_u32 v35, v35, v36, s68
	v_bfe_u32 v36, v38, 16, 1
	v_bfe_u32 v37, v39, 16, 1
	v_bfe_u32 v44, v42, 16, 1
	v_bfe_u32 v45, v43, 16, 1
	v_add3_u32 v43, v43, v45, s68
	v_add3_u32 v42, v42, v44, s68
	v_add3_u32 v37, v39, v37, s68
	v_add3_u32 v36, v38, v36, s68
	v_lshrrev_b32_e32 v38, 16, v36
	v_lshrrev_b32_e32 v39, 16, v37
	v_lshrrev_b32_e32 v36, 16, v42
	v_lshrrev_b32_e32 v37, 16, v43
	v_and_or_b32 v37, v35, s82, v37
	v_and_or_b32 v36, v34, s82, v36
	v_and_or_b32 v35, v41, s82, v39
	v_and_or_b32 v34, v40, s82, v38
	ds_read_b128 v[42:45], v191 offset:32768
	global_store_dwordx4 v[32:33], v[34:37], off
	v_and_b32_e32 v46, 0xffffffc0, v191
	ds_read_b128 v[50:53], v46
	ds_read_b128 v[54:57], v46 offset:16
	ds_read_b128 v[58:61], v46 offset:32
	s_waitcnt lgkmcnt(0)
	global_store_dwordx4 v[32:33], v[50:53], off offset:-192
	global_store_dwordx4 v[32:33], v[54:57], off offset:-128
	global_store_dwordx4 v[32:33], v[58:61], off offset:-64
	v_add_u32_e32 v32, 0x20c00, v192
	ds_read_b32 v40, v32
	s_waitcnt lgkmcnt(1)
	v_and_b32_e32 v35, 0xffff0000, v43
	v_and_b32_e32 v34, 0xffff0000, v42
	v_and_b32_e32 v39, 0xffff0000, v45
	v_and_b32_e32 v38, 0xffff0000, v44
	v_lshlrev_b32_e32 v33, 16, v43
	v_lshlrev_b32_e32 v32, 16, v42
	s_waitcnt lgkmcnt(0)
	v_pk_mul_f32 v[34:35], v[40:41], v[34:35] op_sel_hi:[0,1]
	v_lshlrev_b32_e32 v37, 16, v45
	v_lshlrev_b32_e32 v36, 16, v44
	v_pk_mul_f32 v[38:39], v[40:41], v[38:39] op_sel_hi:[0,1]
	v_pk_mul_f32 v[32:33], v[40:41], v[32:33] op_sel_hi:[0,1]
	v_pk_mul_f32 v[36:37], v[40:41], v[36:37] op_sel_hi:[0,1]
	v_bfe_u32 v41, v39, 16, 1
	v_bfe_u32 v42, v38, 16, 1
	v_bfe_u32 v43, v35, 16, 1
	v_bfe_u32 v44, v34, 16, 1
	v_add3_u32 v44, v34, v44, s68
	v_add3_u32 v43, v35, v43, s68
	v_add3_u32 v34, v38, v42, s68
	v_add3_u32 v35, v39, v41, s68
	v_bfe_u32 v41, v36, 16, 1
	v_bfe_u32 v42, v37, 16, 1
	v_add3_u32 v37, v37, v42, s68
	v_add3_u32 v36, v36, v41, s68
	v_bfe_u32 v38, v32, 16, 1
	v_bfe_u32 v39, v33, 16, 1
	v_lshrrev_b32_e32 v41, 16, v36
	v_lshrrev_b32_e32 v36, 16, v37
	v_add3_u32 v33, v33, v39, s68
	v_add3_u32 v32, v32, v38, s68
	v_and_or_b32 v35, v35, s82, v36
	ds_read_b128 v[36:39], v190 offset:32768
	v_lshrrev_b32_e32 v32, 16, v32
	v_lshrrev_b32_e32 v33, 16, v33
	v_and_or_b32 v34, v34, s82, v41
	v_and_or_b32 v33, v43, s82, v33
	v_and_or_b32 v32, v44, s82, v32
	ds_write_b128 v191, v[32:35] offset:32768
	s_waitcnt lgkmcnt(1)
	v_lshlrev_b32_e32 v33, 16, v37
	v_lshlrev_b32_e32 v32, 16, v36
	v_and_b32_e32 v35, 0xffff0000, v37
	v_and_b32_e32 v34, 0xffff0000, v36
	v_lshlrev_b32_e32 v37, 16, v39
	v_lshlrev_b32_e32 v36, 16, v38
	v_and_b32_e32 v39, 0xffff0000, v39
	v_and_b32_e32 v38, 0xffff0000, v38
	v_pk_mul_f32 v[34:35], v[40:41], v[34:35] op_sel_hi:[0,1]
	v_pk_mul_f32 v[38:39], v[40:41], v[38:39] op_sel_hi:[0,1]
	v_pk_mul_f32 v[32:33], v[40:41], v[32:33] op_sel_hi:[0,1]
	v_pk_mul_f32 v[36:37], v[40:41], v[36:37] op_sel_hi:[0,1]
	v_bfe_u32 v41, v39, 16, 1
	v_bfe_u32 v42, v38, 16, 1
	v_bfe_u32 v43, v35, 16, 1
	v_bfe_u32 v44, v34, 16, 1
	v_add3_u32 v44, v34, v44, s68
	v_add3_u32 v43, v35, v43, s68
	v_add3_u32 v34, v38, v42, s68
	v_add3_u32 v35, v39, v41, s68
	v_bfe_u32 v41, v36, 16, 1
	v_bfe_u32 v42, v37, 16, 1
	v_add3_u32 v37, v37, v42, s68
	v_add3_u32 v36, v36, v41, s68
	v_bfe_u32 v38, v32, 16, 1
	v_bfe_u32 v39, v33, 16, 1
	v_lshrrev_b32_e32 v41, 16, v36
	v_lshrrev_b32_e32 v36, 16, v37
	v_add3_u32 v33, v33, v39, s68
	v_add3_u32 v32, v32, v38, s68
	v_and_or_b32 v35, v35, s82, v36
	ds_read_b128 v[36:39], v161 offset:32768
	v_lshrrev_b32_e32 v32, 16, v32
	v_lshrrev_b32_e32 v33, 16, v33
	v_and_or_b32 v34, v34, s82, v41
	v_and_or_b32 v33, v43, s82, v33
	v_and_or_b32 v32, v44, s82, v32
	ds_write_b128 v190, v[32:35] offset:32768
	s_waitcnt lgkmcnt(1)
	v_lshlrev_b32_e32 v33, 16, v37
	v_lshlrev_b32_e32 v32, 16, v36
	v_and_b32_e32 v35, 0xffff0000, v37
	v_and_b32_e32 v34, 0xffff0000, v36
	v_pk_mul_f32 v[36:37], v[40:41], v[32:33] op_sel_hi:[0,1]
	v_pk_mul_f32 v[32:33], v[40:41], v[34:35] op_sel_hi:[0,1]
	v_lshlrev_b32_e32 v35, 16, v39
	v_lshlrev_b32_e32 v34, 16, v38
	v_and_b32_e32 v39, 0xffff0000, v39
	v_and_b32_e32 v38, 0xffff0000, v38
	v_pk_mul_f32 v[42:43], v[40:41], v[34:35] op_sel_hi:[0,1]
	v_pk_mul_f32 v[34:35], v[40:41], v[38:39] op_sel_hi:[0,1]
	v_bfe_u32 v38, v35, 16, 1
	v_bfe_u32 v44, v32, 16, 1
	v_bfe_u32 v39, v34, 16, 1
	v_bfe_u32 v41, v33, 16, 1
	v_add3_u32 v32, v32, v44, s68
	v_add3_u32 v35, v35, v38, s68
	v_bfe_u32 v38, v36, 16, 1
	v_bfe_u32 v44, v43, 16, 1
	v_add3_u32 v33, v33, v41, s68
	v_add3_u32 v34, v34, v39, s68
	v_bfe_u32 v39, v37, 16, 1
	v_bfe_u32 v41, v42, 16, 1
	v_add3_u32 v44, v43, v44, s68
	v_add3_u32 v36, v36, v38, s68
	v_add3_u32 v43, v42, v41, s68
	v_add3_u32 v37, v37, v39, s68
	v_lshrrev_b32_e32 v41, 16, v36
	v_lshrrev_b32_e32 v36, 16, v44
	v_lshrrev_b32_e32 v42, 16, v37
	v_and_or_b32 v35, v35, s82, v36
	ds_read_b128 v[36:39], v117 offset:32768
	v_lshrrev_b32_e32 v43, 16, v43
	v_and_or_b32 v34, v34, s82, v43
	v_and_or_b32 v33, v33, s82, v42
	v_and_or_b32 v32, v32, s82, v41
	ds_write_b128 v161, v[32:35] offset:32768
	s_waitcnt lgkmcnt(1)
	v_lshlrev_b32_e32 v33, 16, v37
	v_lshlrev_b32_e32 v32, 16, v36
	v_and_b32_e32 v35, 0xffff0000, v37
	v_and_b32_e32 v34, 0xffff0000, v36
	v_lshlrev_b32_e32 v37, 16, v39
	v_lshlrev_b32_e32 v36, 16, v38
	v_and_b32_e32 v39, 0xffff0000, v39
	v_and_b32_e32 v38, 0xffff0000, v38
	v_pk_mul_f32 v[34:35], v[40:41], v[34:35] op_sel_hi:[0,1]
	v_pk_mul_f32 v[38:39], v[40:41], v[38:39] op_sel_hi:[0,1]
	v_pk_mul_f32 v[32:33], v[40:41], v[32:33] op_sel_hi:[0,1]
	v_pk_mul_f32 v[36:37], v[40:41], v[36:37] op_sel_hi:[0,1]
	v_bfe_u32 v40, v39, 16, 1
	v_bfe_u32 v41, v38, 16, 1
	v_bfe_u32 v42, v35, 16, 1
	v_bfe_u32 v43, v34, 16, 1
	v_add3_u32 v43, v34, v43, s68
	v_add3_u32 v42, v35, v42, s68
	v_add3_u32 v34, v38, v41, s68
	v_add3_u32 v35, v39, v40, s68
	v_bfe_u32 v38, v32, 16, 1
	v_bfe_u32 v39, v33, 16, 1
	v_bfe_u32 v40, v36, 16, 1
	v_bfe_u32 v41, v37, 16, 1
	v_add3_u32 v37, v37, v41, s68
	v_add3_u32 v36, v36, v40, s68
	v_add3_u32 v33, v33, v39, s68
	v_add3_u32 v32, v32, v38, s68
	v_lshrrev_b32_e32 v32, 16, v32
	v_lshrrev_b32_e32 v33, 16, v33
	v_lshrrev_b32_e32 v36, 16, v36
	v_lshrrev_b32_e32 v37, 16, v37
	v_and_or_b32 v35, v35, s82, v37
	v_and_or_b32 v34, v34, s82, v36
	v_and_or_b32 v33, v42, s82, v33
	v_and_or_b32 v32, v43, s82, v32
	ds_write_b128 v117, v[32:35] offset:32768
	s_and_saveexec_b64 s[0:1], s[8:9]
	s_cbranch_execz .LBB0_775
	v_lshl_add_u32 v32, v132, 2, 0
	v_add_u32_e32 v32, 0x20e00, v32
	ds_read_b32 v33, v32
	s_waitcnt lgkmcnt(0)
	v_mul_f32_e32 v33, v109, v33
	ds_write_b32 v32, v33
